# prep: wave 7 runs the T inversion at s_setprio 2 (it is the youngest wave and now the longest path between barriers A and C)
# baseline (speedup 1.0000x reference)
; #define WAVE_SYNC() do { asm volatile("s_waitcnt lgkmcnt(0)" ::: "memory"); __builtin_amdgcn_wave_barrier(); } while (0)
; __device__ __forceinline__ void tinv_wave(const float* Aab, bf16_t* Tm, bf16_t* TT, bf16_t* ET, bf16_t* E2T, int lane) {
;     constexpr int LD = 72;
;     const int fr = lane & 15, fq = lane >> 4;
;     const bf16x8 zf = (bf16x8){0, 0, 0, 0, 0, 0, 0, 0};
;     {
;         const u32x4 z = (u32x4){0u, 0u, 0u, 0u};
; #pragma unroll
;         for (int i = 0; i < 9; ++i) { *(u32x4*)(Tm + lane * LD + i * 8) = z; *(u32x4*)(TT + lane * LD + i * 8) = z; }
;     }
;     WAVE_SYNC();
;     {
;         const int q = fq, c = fr; const float* Ab = Aab + (16 * q) * 68 + 16 * q;
;         float d[16];
; #pragma unroll
;         for (int i = 0; i < 16; ++i) {
;             float a = (i == c) ? 1.0f : 0.0f;
; #pragma unroll
;             for (int m = 0; m < i; ++m) a -= Ab[i * 68 + m] * d[m];
;             d[i] = a;
;             if ((i & 3) == 3) __builtin_amdgcn_sched_barrier(0);
;         }
.LBB0_238:
	s_and_b64 vcc, exec, s[20:21]
	s_cbranch_vccz .LBB0_256
	s_setprio 2
	v_mul_u32_u24_e32 v24, 0x48, v68
	v_lshlrev_b32_e32 v24, 1, v24
	v_add_u32_e32 v25, 0, v24
	v_add_u32_e32 v24, s66, v24
	ds_write_b128 v25, v[192:195] offset:17408
	ds_write_b128 v24, v[192:195]
	ds_write_b128 v25, v[192:195] offset:17424
	ds_write_b128 v24, v[192:195] offset:16
	ds_write_b128 v25, v[192:195] offset:17440
	ds_write_b128 v24, v[192:195] offset:32
	ds_write_b128 v25, v[192:195] offset:17456
	ds_write_b128 v24, v[192:195] offset:48
	ds_write_b128 v25, v[192:195] offset:17472
	ds_write_b128 v24, v[192:195] offset:64
	ds_write_b128 v25, v[192:195] offset:17488
	ds_write_b128 v24, v[192:195] offset:80
	ds_write_b128 v25, v[192:195] offset:17504
	ds_write_b128 v24, v[192:195] offset:96
	ds_write_b128 v25, v[192:195] offset:17520
	ds_write_b128 v24, v[192:195] offset:112
	ds_write_b128 v25, v[192:195] offset:17536
	ds_write_b128 v24, v[192:195] offset:128
	v_mul_u32_u24_e32 v24, 0x110, v141
	v_lshlrev_b32_e32 v25, 2, v141
	v_add3_u32 v69, 0, v24, v25
	s_waitcnt lgkmcnt(0)
	ds_read_b32 v27, v69 offset:272
	ds_read_b64 v[36:37], v69 offset:544
	ds_read_b96 v[24:26], v69 offset:816
	v_cmp_eq_u32_e32 vcc, 0, v185
	s_waitcnt lgkmcnt(0)
	v_mov_b32_e32 v66, v25
	v_cndmask_b32_e64 v30, 0, 1.0, vcc
	v_cmp_eq_u32_e32 vcc, 3, v185
	v_mov_b32_e32 v67, v26
	v_mov_b32_e32 v26, v36
	v_cndmask_b32_e64 v28, 0, 1.0, vcc
	v_cmp_eq_u32_e32 vcc, 1, v185
	v_fma_f32 v87, -v30, v24, v28
	s_nop 0
	v_cndmask_b32_e64 v25, 0, 1.0, vcc
	v_cmp_eq_u32_e32 vcc, 2, v185
	s_nop 1
	v_cndmask_b32_e64 v24, 0, 1.0, vcc
	v_pk_fma_f32 v[32:33], v[30:31], v[26:27], v[24:25] op_sel_hi:[0,1,1] neg_lo:[1,0,0] neg_hi:[1,0,0]
	v_mov_b32_e32 v31, v33
	ds_read_b128 v[26:29], v69 offset:1088
	ds_read_b96 v[34:36], v69 offset:1360
	ds_read_b128 v[42:45], v69 offset:1632
	v_cmp_eq_u32_e32 vcc, 4, v185
	s_waitcnt lgkmcnt(2)
	v_pk_mul_f32 v[24:25], v[30:31], v[26:27]
	v_cndmask_b32_e64 v38, 0, 1.0, vcc
	v_sub_f32_e32 v24, v38, v24
	v_cmp_eq_u32_e32 vcc, 5, v185
	v_sub_f32_e32 v126, v24, v25
	ds_read_b64 v[38:39], v69 offset:1648
	v_cndmask_b32_e64 v24, 0, 1.0, vcc
	v_cmp_eq_u32_e32 vcc, 6, v185
	s_waitcnt lgkmcnt(2)
	v_fma_f32 v143, -v30, v34, v24
	s_waitcnt lgkmcnt(1)
	v_pk_mul_f32 v[24:25], v[30:31], v[42:43]
	v_cndmask_b32_e64 v26, 0, 1.0, vcc
	v_mov_b32_e32 v88, v35
	v_sub_f32_e32 v24, v26, v24
	v_add_u32_e32 v34, 0x77c, v69
	v_add_u32_e32 v35, 0x784, v69
	v_add_u32_e32 v27, 0x55c, v69
	v_sub_f32_e32 v145, v24, v25
	ds_read_b96 v[24:26], v69 offset:1904
	ds_read2_b32 v[42:43], v27 offset1:1
	ds_read2_b32 v[90:91], v34 offset1:1
	ds_read2_b32 v[34:35], v35 offset1:1
	v_cmp_eq_u32_e32 vcc, 7, v185
	v_mov_b32_e32 v89, v36
	s_waitcnt lgkmcnt(3)
	v_mov_b32_e32 v92, v25
	v_cndmask_b32_e64 v27, 0, 1.0, vcc
	v_mov_b32_e32 v93, v26
	v_fma_f32 v190, -v30, v24, v27
	ds_read_b128 v[46:49], v69 offset:2176
	ds_read_b128 v[24:27], v69 offset:2192
	ds_read_b96 v[54:56], v69 offset:2448
	ds_read_b128 v[50:53], v69 offset:2720
	v_cmp_eq_u32_e32 vcc, 8, v185
	v_add_u32_e32 v58, 0x9a4, v69
	s_waitcnt lgkmcnt(3)
	v_pk_mul_f32 v[46:47], v[30:31], v[46:47]
	v_cndmask_b32_e64 v36, 0, 1.0, vcc
	v_sub_f32_e32 v36, v36, v46
	v_cmp_eq_u32_e32 vcc, 9, v185
	v_sub_f32_e32 v191, v36, v47
	s_waitcnt lgkmcnt(0)
	v_pk_mul_f32 v[50:51], v[30:31], v[50:51]
	v_cndmask_b32_e64 v36, 0, 1.0, vcc
	v_cmp_eq_u32_e32 vcc, 10, v185
	v_fma_f32 v196, -v30, v54, v36
	v_add_u32_e32 v59, 0x9ac, v69
	v_cndmask_b32_e64 v54, 0, 1.0, vcc
	v_sub_f32_e32 v50, v54, v50
	v_add_u32_e32 v60, 0xbbc, v69
	v_mov_b32_e32 v46, v55
	v_mov_b32_e32 v47, v56
	v_add_u32_e32 v36, 0x99c, v69
	v_sub_f32_e32 v197, v50, v51
	v_add_u32_e32 v61, 0xbc4, v69
	v_add_u32_e32 v62, 0xbcc, v69
	v_add_u32_e32 v63, 0xbd4, v69
	ds_read_b64 v[50:51], v69 offset:2752
	ds_read_b128 v[54:57], v69 offset:2736
	ds_read2_b32 v[94:95], v60 offset1:1
	ds_read2_b32 v[96:97], v61 offset1:1
	ds_read2_b32 v[98:99], v59 offset1:1
	ds_read2_b32 v[100:101], v58 offset1:1
	ds_read_b96 v[58:60], v69 offset:2992
	ds_read2_b32 v[102:103], v36 offset1:1
	ds_read2_b32 v[104:105], v62 offset1:1
	ds_read2_b32 v[106:107], v63 offset1:1
	v_cmp_eq_u32_e32 vcc, 11, v185
	s_waitcnt lgkmcnt(3)
	v_mov_b32_e32 v108, v59
	v_mov_b32_e32 v109, v60
	v_cndmask_b32_e64 v36, 0, 1.0, vcc
	v_fma_f32 v198, -v30, v58, v36
	ds_read_b128 v[58:61], v69 offset:3264
	ds_read_b128 v[62:65], v69 offset:3280
	ds_read_b128 v[70:73], v69 offset:3296
	ds_read_b96 v[74:76], v69 offset:3536
	v_cmp_eq_u32_e32 vcc, 12, v185
	v_add_u32_e32 v83, 0x100c, v69
	s_waitcnt lgkmcnt(3)
	v_pk_mul_f32 v[58:59], v[30:31], v[58:59]
	v_cndmask_b32_e64 v36, 0, 1.0, vcc
	v_cmp_eq_u32_e32 vcc, 13, v185
	v_sub_f32_e32 v31, v36, v58
	v_sub_f32_e32 v31, v31, v59
	v_cndmask_b32_e64 v36, 0, 1.0, vcc
	s_waitcnt lgkmcnt(0)
	v_mov_b32_e32 v58, v75
	v_mov_b32_e32 v59, v76
	v_fma_f32 v199, -v30, v74, v36
	ds_read_b128 v[74:77], v69 offset:3808
	ds_read_b96 v[84:86], v69 offset:4080
	ds_read_b128 v[78:81], v69 offset:3824
	v_cmp_eq_u32_e32 vcc, 14, v185
	v_add_u32_e32 v36, 0xddc, v69
	v_fma_f32 v189, -v33, v37, v32
	v_cndmask_b32_e64 v82, 0, 1.0, vcc
	s_waitcnt lgkmcnt(2)
	v_fma_f32 v74, -v30, v74, v82
	v_cndmask_b32_e64 v82, 0, 1.0, s[18:19]
	v_fma_f32 v200, -v33, v75, v74
	ds_read2_b32 v[74:75], v36 offset1:1
	s_waitcnt lgkmcnt(2)
; __device__ __forceinline__ void tinv_wave(const float* Aab, bf16_t* Tm, bf16_t* TT, bf16_t* ET, bf16_t* E2T, int lane) {
;     ...
; #pragma unroll
;         for (int i = 0; i < 16; ++i) {
;             float a = (i == c) ? 1.0f : 0.0f;
; #pragma unroll
;             for (int m = 0; m < i; ++m) a -= Ab[i * 68 + m] * d[m];
;             d[i] = a;
;             if ((i & 3) == 3) __builtin_amdgcn_sched_barrier(0);
;         }
	v_fma_f32 v36, -v30, v84, v82
	v_fma_f32 v201, -v33, v85, v36
	v_add_u32_e32 v36, 0xffc, v69
	v_add_u32_e32 v82, 0x1004, v69
	v_add_u32_e32 v84, 0x1014, v69
	ds_read2_b32 v[110:111], v36 offset1:1
	ds_read2_b32 v[112:113], v82 offset1:1
	ds_read2_b32 v[114:115], v83 offset1:1
	ds_read2_b32 v[116:117], v84 offset1:1
	v_add_u32_e32 v36, 0x101c, v69
	v_mov_b32_e32 v188, v33
	ds_read2_b32 v[118:119], v36 offset1:1
	v_pk_mul_f32 v[36:37], v[188:189], v[66:67]
	v_pk_mul_f32 v[66:67], v[188:189], v[88:89]
	v_add_u32_e32 v154, 0xde4, v69
	v_add_u32_e32 v152, 0xdec, v69
	v_add_u32_e32 v150, 0xdf4, v69
	v_add_u32_e32 v148, 0xdfc, v69
	v_sub_f32_e32 v32, v87, v36
	v_sub_f32_e32 v36, v143, v66
	v_add_u32_e32 v202, 0x1024, v69
	ds_read_b64 v[146:147], v69 offset:3856
	ds_read_b128 v[82:85], v69 offset:3840
	ds_read2_b32 v[148:149], v148 offset1:1
	ds_read2_b32 v[150:151], v150 offset1:1
	ds_read2_b32 v[152:153], v152 offset1:1
	ds_read2_b32 v[154:155], v154 offset1:1
	v_sub_f32_e32 v69, v36, v67
	v_pk_mul_f32 v[66:67], v[188:189], v[92:93]
	v_pk_mul_f32 v[46:47], v[188:189], v[46:47]
	v_sub_f32_e32 v36, v190, v66
	v_sub_f32_e32 v66, v36, v67
	v_sub_f32_e32 v36, v196, v46
	v_sub_f32_e32 v67, v36, v47
	v_pk_mul_f32 v[46:47], v[188:189], v[108:109]
	v_pk_mul_f32 v[58:59], v[188:189], v[58:59]
	v_sub_f32_e32 v36, v198, v46
	v_sub_f32_e32 v87, v36, v47
	v_sub_f32_e32 v47, v32, v37
	v_mov_b32_e32 v46, v189
	v_pk_mul_f32 v[28:29], v[46:47], v[28:29]
	v_pk_mul_f32 v[36:37], v[46:47], v[60:61]
	v_sub_f32_e32 v28, v126, v28
	v_pk_mul_f32 v[48:49], v[46:47], v[48:49]
	v_pk_mul_f32 v[52:53], v[46:47], v[52:53]
	v_pk_mul_f32 v[44:45], v[46:47], v[44:45]
	v_sub_f32_e32 v29, v28, v29
	v_mov_b32_e32 v28, v47
	v_sub_f32_e32 v31, v31, v36
	v_sub_f32_e32 v32, v199, v58
	v_sub_f32_e32 v36, v191, v48
	v_sub_f32_e32 v48, v197, v52
	v_sub_f32_e32 v44, v145, v44
	v_pk_mul_f32 v[42:43], v[28:29], v[42:43]
	v_sub_f32_e32 v32, v32, v59
	v_pk_mul_f32 v[58:59], v[46:47], v[76:77]
	v_sub_f32_e32 v46, v44, v45
	v_sub_f32_e32 v52, v36, v49
	v_sub_f32_e32 v53, v48, v53
	v_sub_f32_e32 v31, v31, v37
	s_waitcnt lgkmcnt(11)
	v_pk_mul_f32 v[36:37], v[28:29], v[74:75]
	v_pk_mul_f32 v[44:45], v[28:29], v[102:103]
	v_sub_f32_e32 v42, v69, v42
	v_pk_mul_f32 v[48:49], v[28:29], v[90:91]
	v_sub_f32_e32 v58, v200, v58
	v_sub_f32_e32 v32, v32, v36
	v_sub_f32_e32 v36, v67, v44
	v_sub_f32_e32 v44, v66, v48
	v_sub_f32_e32 v43, v42, v43
	v_mov_b32_e32 v42, v29
	v_sub_f32_e32 v58, v58, v59
	v_sub_f32_e32 v59, v44, v49
	v_sub_f32_e32 v61, v36, v45
	v_pk_mul_f32 v[44:45], v[28:29], v[94:95]
	v_pk_mul_f32 v[38:39], v[42:43], v[38:39]
	v_fma_f32 v60, -v189, v86, v201
	v_sub_f32_e32 v36, v87, v44
	s_waitcnt lgkmcnt(10)
	v_pk_mul_f32 v[48:49], v[28:29], v[110:111]
	v_pk_mul_f32 v[24:25], v[42:43], v[24:25]
	v_sub_f32_e32 v38, v46, v38
	v_sub_f32_e32 v66, v36, v45
	v_sub_f32_e32 v32, v32, v37
	v_pk_mul_f32 v[36:37], v[42:43], v[78:79]
	v_sub_f32_e32 v28, v60, v48
	v_sub_f32_e32 v24, v52, v24
	v_sub_f32_e32 v39, v38, v39
	v_mov_b32_e32 v38, v43
	v_pk_mul_f32 v[44:45], v[42:43], v[62:63]
	v_sub_f32_e32 v36, v58, v36
	v_sub_f32_e32 v28, v28, v49
	v_pk_mul_f32 v[48:49], v[42:43], v[54:55]
	v_sub_f32_e32 v42, v24, v25
	s_waitcnt lgkmcnt(0)
; __device__ __forceinline__ unsigned pk_bf16(float lo, float hi) { const f32x2 v = (f32x2){lo, hi}; const bf16v2 b = __builtin_convertvector(v, bf16v2); return __builtin_bit_cast(unsigned, b); }
; __device__ __forceinline__ bf16_t f2bf(float f) { return (bf16_t)(pk_bf16(f, 0.f) & 0xffffu); }
; #define LDS_BARRIER() do { asm volatile("s_waitcnt lgkmcnt(0)" ::: "memory"); __builtin_amdgcn_s_barrier(); asm volatile("" ::: "memory"); } while (0)
; #define WAVE_SYNC() do { asm volatile("s_waitcnt lgkmcnt(0)" ::: "memory"); __builtin_amdgcn_wave_barrier(); } while (0)
; #define P() (*(const Params*)(cp = cp_launder(cp)))
; __device__ __forceinline__ void tinv_wave(const float* Aab, bf16_t* Tm, bf16_t* TT, bf16_t* ET, bf16_t* E2T, int lane) {
;     ...
; #pragma unroll
;         for (int i = 0; i < 16; ++i) {
;             float a = (i == c) ? 1.0f : 0.0f;
; #pragma unroll
;             for (int m = 0; m < i; ++m) a -= Ab[i * 68 + m] * d[m];
;             d[i] = a;
;             if ((i & 3) == 3) __builtin_amdgcn_sched_barrier(0);
;         }
;         u32x4 lo, hi;
;         lo.x = pk_bf16(d[0], d[1]); lo.y = pk_bf16(d[2], d[3]); lo.z = pk_bf16(d[4], d[5]); lo.w = pk_bf16(d[6], d[7]);
;         hi.x = pk_bf16(d[8], d[9]); hi.y = pk_bf16(d[10], d[11]); hi.z = pk_bf16(d[12], d[13]); hi.w = pk_bf16(d[14], d[15]);
;         *(u32x4*)(TT + (16 * q + c) * LD + 16 * q) = lo; *(u32x4*)(TT + (16 * q + c) * LD + 16 * q + 8) = hi;
; #pragma unroll
;         for (int i = 0; i < 16; ++i) Tm[(16 * q + i) * LD + 16 * q + c] = f2bf(d[i]);
;     }
;     WAVE_SYNC();
;     LDS_BARRIER();
; #pragma unroll
;     for (int P = 0; P < 2; ++P) {
;         const int lo = 2 * P, hi = 2 * P + 1;
;         const bf16x8 a = fq < 2 ? cvt_frag8(Aab + (16 * hi + fr) * 68 + 16 * lo + 8 * fq) : zf;
;         const bf16x8 b = fq < 2 ? *(const bf16x8*)(TT + (16 * lo + fr) * LD + 16 * lo + 8 * fq) : zf;
	v_pk_mul_f32 v[24:25], v[38:39], v[154:155]
	v_pk_mul_f32 v[34:35], v[38:39], v[34:35]
	v_sub_f32_e32 v31, v31, v44
	v_sub_f32_e32 v44, v53, v48
	v_sub_f32_e32 v24, v32, v24
	v_sub_f32_e32 v32, v36, v37
	v_pk_mul_f32 v[36:37], v[38:39], v[100:101]
	v_sub_f32_e32 v34, v59, v34
	v_sub_f32_e32 v46, v44, v49
	v_sub_f32_e32 v31, v31, v45
	v_sub_f32_e32 v36, v61, v36
	v_sub_f32_e32 v45, v34, v35
	v_mov_b32_e32 v44, v39
	v_sub_f32_e32 v52, v36, v37
	v_pk_mul_f32 v[36:37], v[38:39], v[96:97]
	v_pk_mul_f32 v[26:27], v[44:45], v[26:27]
	v_sub_f32_e32 v36, v66, v36
	v_sub_f32_e32 v26, v42, v26
	v_sub_f32_e32 v53, v36, v37
	v_pk_mul_f32 v[34:35], v[44:45], v[64:65]
	v_pk_mul_f32 v[36:37], v[38:39], v[112:113]
	v_sub_f32_e32 v49, v26, v27
	v_mov_b32_e32 v48, v45
	v_sub_f32_e32 v31, v31, v34
	v_sub_f32_e32 v34, v24, v25
	v_pk_mul_f32 v[24:25], v[44:45], v[80:81]
	v_sub_f32_e32 v28, v28, v36
	v_pk_mul_f32 v[26:27], v[48:49], v[152:153]
	v_sub_f32_e32 v24, v32, v24
	v_sub_f32_e32 v28, v28, v37
	v_pk_mul_f32 v[36:37], v[44:45], v[56:57]
	v_sub_f32_e32 v31, v31, v35
	v_sub_f32_e32 v26, v34, v26
	v_pk_mul_f32 v[34:35], v[48:49], v[104:105]
	v_sub_f32_e32 v32, v46, v36
	v_sub_f32_e32 v36, v24, v25
	v_pk_mul_f32 v[24:25], v[48:49], v[98:99]
	v_sub_f32_e32 v34, v53, v34
	v_sub_f32_e32 v32, v32, v37
	v_sub_f32_e32 v24, v52, v24
	v_sub_f32_e32 v37, v34, v35
	v_pk_mul_f32 v[34:35], v[48:49], v[114:115]
	v_sub_f32_e32 v53, v24, v25
	v_mov_b32_e32 v52, v49
	v_sub_f32_e32 v28, v28, v34
	v_sub_f32_e32 v28, v28, v35
	v_pk_mul_f32 v[34:35], v[52:53], v[50:51]
	v_pk_mul_f32 v[24:25], v[52:53], v[70:71]
	v_sub_f32_e32 v32, v32, v34
	v_sub_f32_e32 v24, v31, v24
	v_sub_f32_e32 v31, v26, v27
	v_pk_mul_f32 v[26:27], v[52:53], v[82:83]
	v_sub_f32_e32 v51, v32, v35
	v_mov_b32_e32 v50, v53
	v_sub_f32_e32 v26, v36, v26
	v_sub_f32_e32 v34, v24, v25
	v_pk_mul_f32 v[24:25], v[50:51], v[150:151]
	v_mov_b32_e32 v54, v51
	v_sub_f32_e32 v24, v31, v24
	v_sub_f32_e32 v31, v26, v27
	v_pk_mul_f32 v[26:27], v[50:51], v[106:107]
	v_sub_f32_e32 v32, v24, v25
	v_sub_f32_e32 v26, v37, v26
	v_sub_f32_e32 v55, v26, v27
	v_pk_mul_f32 v[26:27], v[54:55], v[72:73]
	v_mov_b32_e32 v56, v55
	v_sub_f32_e32 v26, v34, v26
	v_sub_f32_e32 v57, v26, v27
	v_pk_mul_f32 v[26:27], v[56:57], v[148:149]
	v_pk_mul_f32 v[24:25], v[54:55], v[84:85]
	v_sub_f32_e32 v26, v32, v26
	v_sub_f32_e32 v59, v26, v27
	ds_read2_b32 v[26:27], v202 offset1:1
	v_sub_f32_e32 v24, v31, v24
	v_pk_mul_f32 v[34:35], v[50:51], v[116:117]
	v_mov_b32_e32 v58, v57
	v_sub_f32_e32 v28, v28, v34
	v_sub_f32_e32 v31, v24, v25
	v_pk_mul_f32 v[24:25], v[58:59], v[146:147]
	v_sub_f32_e32 v28, v28, v35
	v_sub_f32_e32 v24, v31, v24
	v_pk_mul_f32 v[34:35], v[56:57], v[118:119]
	v_sub_f32_e32 v61, v24, v25
	v_sub_f32_e32 v28, v28, v34
	v_mov_b32_e32 v60, v59
	v_sub_f32_e32 v28, v28, v35
	s_waitcnt lgkmcnt(0)
	v_pk_mul_f32 v[24:25], v[60:61], v[26:27]
	s_nop 0
	v_sub_f32_e32 v24, v28, v24
	v_sub_f32_e32 v28, v24, v25
	v_mul_u32_u24_e32 v31, 0x90, v68
	v_lshlrev_b32_e32 v32, 1, v141
	v_cvt_pk_bf16_f32 v24, v30, v33
	v_cvt_pk_bf16_f32 v25, v189, v47
	v_cvt_pk_bf16_f32 v26, v29, v43
	v_cvt_pk_bf16_f32 v27, v39, v45
	v_add3_u32 v31, s66, v31, v32
	v_cvt_pk_bf16_f32 v34, v49, v53
	v_cvt_pk_bf16_f32 v35, v51, v55
	v_cvt_pk_bf16_f32 v36, v57, v59
	v_cvt_pk_bf16_f32 v37, v61, v28
	ds_write_b128 v31, v[24:27]
	ds_write_b128 v31, v[34:37] offset:16
	v_lshlrev_b32_e32 v24, 1, v185
	v_add3_u32 v24, 0, v32, v24
	v_cvt_pk_bf16_f32 v25, v30, s0
	v_mad_u32_u24 v26, v141, s50, v24
	ds_write_b16 v26, v25 offset:17408
	v_cvt_pk_bf16_f32 v25, v33, s0
	ds_write_b16 v26, v25 offset:17552
	v_cvt_pk_bf16_f32 v25, v189, s0
	ds_write_b16 v26, v25 offset:17696
	v_cvt_pk_bf16_f32 v25, v47, s0
	ds_write_b16 v26, v25 offset:17840
	v_cvt_pk_bf16_f32 v25, v29, s0
	ds_write_b16 v26, v25 offset:17984
	v_cvt_pk_bf16_f32 v25, v43, s0
	ds_write_b16 v26, v25 offset:18128
	v_cvt_pk_bf16_f32 v25, v39, s0
	ds_write_b16 v26, v25 offset:18272
	v_cvt_pk_bf16_f32 v25, v45, s0
	ds_write_b16 v26, v25 offset:18416
	v_cvt_pk_bf16_f32 v25, v49, s0
	ds_write_b16 v26, v25 offset:18560
	v_cvt_pk_bf16_f32 v25, v53, s0
	ds_write_b16 v26, v25 offset:18704
	v_cvt_pk_bf16_f32 v25, v51, s0
	ds_write_b16 v26, v25 offset:18848
	v_cvt_pk_bf16_f32 v25, v55, s0
	ds_write_b16 v26, v25 offset:18992
	v_cvt_pk_bf16_f32 v25, v57, s0
	ds_write_b16 v26, v25 offset:19136
	v_cvt_pk_bf16_f32 v25, v59, s0
	ds_write_b16 v26, v25 offset:19280
	v_cvt_pk_bf16_f32 v25, v61, s0
	ds_write_b16 v26, v25 offset:19424
	v_or_b32_e32 v26, 15, v68
	v_cvt_pk_bf16_f32 v25, v28, s0
	v_mad_u32_u24 v24, v26, s50, v24
	ds_write_b16 v24, v25 offset:17408
	s_waitcnt lgkmcnt(0)
	s_waitcnt lgkmcnt(0)
	v_cmp_gt_u32_e32 vcc, 32, v68
	v_lshlrev_b32_e32 v35, 5, v137
	v_mov_b32_e32 v24, 0
	v_mov_b32_e32 v28, 0
	v_mov_b32_e32 v29, 0
	v_mov_b32_e32 v30, 0
	v_mov_b32_e32 v31, 0
	s_and_saveexec_b64 s[18:19], vcc
	s_cbranch_execz .LBB0_241
	v_or_b32_e32 v25, 16, v68
	v_mul_u32_u24_e32 v25, 0x110, v25
	v_add3_u32 v25, 0, v25, v35
	ds_read_b128 v[28:31], v25
	ds_read_b128 v[36:39], v25 offset:16
	s_waitcnt lgkmcnt(1)
	v_cvt_pk_bf16_f32 v28, v28, v29
	v_cvt_pk_bf16_f32 v29, v30, v31
	s_waitcnt lgkmcnt(0)
	v_cvt_pk_bf16_f32 v30, v36, v37
	v_cvt_pk_bf16_f32 v31, v38, v39

; __device__ __forceinline__ bf16_t f2bf(float f) { return (bf16_t)(pk_bf16(f, 0.f) & 0xffffu); }
; __device__ __forceinline__ void st_bf4(bf16_t* p, f32x4 v) { u32x2 u; u.x = pk_bf16(v[0], v[1]); u.y = pk_bf16(v[2], v[3]); *(u32x2*)p = u; }
; __device__ __forceinline__ void tinv_wave(const float* Aab, bf16_t* Tm, bf16_t* TT, bf16_t* ET, bf16_t* E2T, int lane) {
;     ...
;     for (int P = 0; P < 2; ++P) {
;         const int lo = 2 * P, hi = 2 * P + 1;
;         const bf16x8 a = fq < 2 ? cvt_frag8(Aab + (16 * hi + fr) * 68 + 16 * lo + 8 * fq) : zf;
;         const bf16x8 b = fq < 2 ? *(const bf16x8*)(TT + (16 * lo + fr) * LD + 16 * lo + 8 * fq) : zf;
;         const f32x4 e = MFMA16(a, b, ((f32x4){0.f, 0.f, 0.f, 0.f}));
;         st_bf4(ET + (P * 16 + fr) * 24 + 4 * fq, e);
;     }
;     WAVE_SYNC();
; #pragma unroll
;     for (int P = 0; P < 2; ++P) {
;         const int lo = 2 * P, hi = 2 * P + 1;
;         const bf16x8 a = fq < 2 ? *(const bf16x8*)(Tm + (16 * hi + fr) * LD + 16 * hi + 8 * fq) : zf;
;         const bf16x8 b = fq < 2 ? *(const bf16x8*)(ET + (P * 16 + fr) * 24 + 8 * fq) : zf;
;         const f32x4 t = -MFMA16(a, b, ((f32x4){0.f, 0.f, 0.f, 0.f}));
;         st_bf4(TT + (16 * lo + fr) * LD + 16 * hi + 4 * fq, t);
; #pragma unroll
;         for (int j = 0; j < 4; ++j) Tm[(16 * hi + 4 * fq + j) * LD + 16 * lo + fr] = f2bf(t[j]);
;     }
;     WAVE_SYNC();
; #pragma unroll
;     for (int mi = 0; mi < 2; ++mi) {
;         const bf16x8 a = cvt_frag8(Aab + (32 + 16 * mi + fr) * 68 + 8 * fq);
; #pragma unroll
;         for (int nc = 0; nc < 2; ++nc) {
;             const bf16x8 b = *(const bf16x8*)(TT + (16 * nc + fr) * LD + 8 * fq);
;             const f32x4 e = MFMA16(a, b, ((f32x4){0.f, 0.f, 0.f, 0.f}));
;             st_bf4(E2T + (16 * nc + fr) * 40 + 16 * mi + 4 * fq, e);
;         }
;     }
;     WAVE_SYNC();
; #pragma unroll
;     for (int mi = 0; mi < 2; ++mi) {
;         const bf16x8 a = *(const bf16x8*)(Tm + (32 + 16 * mi + fr) * LD + 32 + 8 * fq);
; #pragma unroll
;         for (int nc = 0; nc < 2; ++nc) {
;             const bf16x8 b = *(const bf16x8*)(E2T + (16 * nc + fr) * 40 + 8 * fq);
;             const f32x4 t = -MFMA16(a, b, ((f32x4){0.f, 0.f, 0.f, 0.f}));
; #pragma unroll
;             for (int j = 0; j < 4; ++j) Tm[(32 + 16 * mi + 4 * fq + j) * LD + 16 * nc + fr] = f2bf(t[j]);
;         }
;     }
;     LDS_BARRIER();
.LBB0_245:
	s_or_b64 exec, exec, s[18:19]
	v_mov_b32_e32 v25, 0
	v_mov_b32_e32 v26, 0
	v_mov_b32_e32 v27, 0
	s_and_saveexec_b64 s[18:19], vcc
	ds_read_b128 v[24:27], v37 offset:4672
	s_or_b64 exec, exec, s[18:19]
	s_waitcnt lgkmcnt(0)
	v_mfma_f32_16x16x32_bf16 v[24:27], v[28:31], v[24:27], 0
	v_mul_u32_u24_e32 v37, 48, v185
	v_add_u32_e32 v28, v37, v33
	v_or_b32_e32 v35, 16, v185
	v_mov_b32_e32 v29, 0
	v_mov_b32_e32 v30, 0
	s_nop 2
	v_cvt_pk_bf16_f32 v24, v24, v25
	v_cvt_pk_bf16_f32 v25, v26, v27
	ds_write_b64 v28, v[24:25] offset:768
	s_waitcnt lgkmcnt(0)
	v_mov_b32_e32 v24, 0
	v_mov_b32_e32 v28, 0
	v_mov_b32_e32 v31, 0
	s_and_saveexec_b64 s[18:19], vcc
	v_mul_u32_u24_e32 v25, 0x90, v35
	v_add3_u32 v25, 0, v25, v34
	ds_read_b128 v[28:31], v25 offset:17440
	s_or_b64 exec, exec, s[18:19]
	v_add_u32_e32 v25, s67, v34
	v_add_u32_e32 v38, v25, v37
	v_mov_b32_e32 v25, 0
	v_mov_b32_e32 v26, 0
	v_mov_b32_e32 v27, 0
	s_and_saveexec_b64 s[18:19], vcc
	ds_read_b128 v[24:27], v38
	s_or_b64 exec, exec, s[18:19]
	s_waitcnt lgkmcnt(0)
	v_mfma_f32_16x16x32_bf16 v[24:27], v[28:31], v[24:27], 0
	v_lshlrev_b32_e32 v39, 1, v139
	v_lshl_add_u32 v37, v185, 1, 0
	v_add3_u32 v39, s66, v32, v39
	v_mul_u32_u24_e32 v36, 0x90, v36
	v_mov_b32_e32 v31, 0
	s_nop 2
	v_xor_b32_e32 v28, 0x80000000, v24
	v_xor_b32_e32 v29, 0x80000000, v25
	v_cvt_pk_bf16_f32 v28, v28, v29
	v_xor_b32_e32 v29, 0x80000000, v26
	v_xor_b32_e32 v30, 0x80000000, v27
	v_cvt_pk_bf16_f32 v29, v29, v30
	ds_write_b64 v39, v[28:29] offset:32
	v_cvt_pk_bf16_f32 v24, -v24, s0
	v_mad_u32_u24 v28, v137, s68, v37
	ds_write_b16 v28, v24 offset:19712
	v_cvt_pk_bf16_f32 v24, -v25, s0
	ds_write_b16 v28, v24 offset:19856
	v_cvt_pk_bf16_f32 v24, -v26, s0
	ds_write_b16 v28, v24 offset:20000
	v_cvt_pk_bf16_f32 v24, -v27, s0
	ds_write_b16 v28, v24 offset:20144
	v_mov_b32_e32 v24, 0
	v_mov_b32_e32 v28, 0
	v_mov_b32_e32 v29, 0
	v_mov_b32_e32 v30, 0
	s_and_saveexec_b64 s[18:19], vcc
	v_add3_u32 v25, 0, v36, v34
	ds_read_b128 v[28:31], v25 offset:17504
	s_or_b64 exec, exec, s[18:19]
	v_mov_b32_e32 v25, 0
	v_mov_b32_e32 v26, 0
	v_mov_b32_e32 v27, 0
	s_and_saveexec_b64 s[18:19], vcc
	ds_read_b128 v[24:27], v38 offset:768
	s_or_b64 exec, exec, s[18:19]
	s_waitcnt lgkmcnt(0)
	v_mfma_f32_16x16x32_bf16 v[24:27], v[28:31], v[24:27], 0
	v_mul_u32_u24_e32 v34, 0x240, v137
	v_add_u32_e32 v37, v37, v34
	v_mad_u32_u24 v38, v185, s48, 0
	v_lshl_add_u32 v34, v41, 2, v38
	v_mad_u32_u24 v46, v185, s69, v33
	s_nop 2
	v_xor_b32_e32 v28, 0x80000000, v24
	v_xor_b32_e32 v29, 0x80000000, v25
	v_xor_b32_e32 v30, 0x80000000, v26
	v_cvt_pk_bf16_f32 v28, v28, v29
	v_xor_b32_e32 v29, 0x80000000, v27
	v_cvt_pk_bf16_f32 v29, v30, v29
	v_cvt_pk_bf16_f32 v24, -v24, s0
	ds_write_b64 v39, v[28:29] offset:4704
	ds_write_b16 v37, v24 offset:24384
	v_cvt_pk_bf16_f32 v24, -v25, s0
	ds_write_b16 v37, v24 offset:24528
	v_cvt_pk_bf16_f32 v24, -v26, s0
	ds_write_b16 v37, v24 offset:24672
	v_cvt_pk_bf16_f32 v24, -v27, s0
	ds_write_b16 v37, v24 offset:24816
	s_waitcnt lgkmcnt(0)
	s_barrier
	ds_read_b128 v[24:27], v34 offset:8704
	ds_read_b128 v[28:31], v34 offset:8720
	v_add_u32_e32 v39, s66, v40
	v_add_u32_e32 v32, v39, v32
	ds_read_b128 v[42:45], v32
	s_waitcnt lgkmcnt(2)
	v_cvt_pk_bf16_f32 v24, v24, v25
	v_cvt_pk_bf16_f32 v25, v26, v27
	s_waitcnt lgkmcnt(1)
	v_cvt_pk_bf16_f32 v26, v28, v29
	v_cvt_pk_bf16_f32 v27, v30, v31
	s_waitcnt lgkmcnt(0)
	s_nop 0
	v_mfma_f32_16x16x32_bf16 v[28:31], v[24:27], v[42:45], 0
	s_nop 7
	v_cvt_pk_bf16_f32 v28, v28, v29
	v_cvt_pk_bf16_f32 v29, v30, v31
	ds_write_b64 v46, v[28:29]
	v_mad_u32_u24 v28, v35, s50, v39
	ds_read_b128 v[28:31], v28
	v_mad_u32_u24 v39, v185, s69, v184
	s_waitcnt lgkmcnt(0)
	v_mfma_f32_16x16x32_bf16 v[24:27], v[24:27], v[28:31], 0
	v_add_u32_e32 v47, v33, v39
	s_nop 6
	v_cvt_pk_bf16_f32 v24, v24, v25
	v_cvt_pk_bf16_f32 v25, v26, v27
	ds_write_b64 v47, v[24:25]
	ds_read_b128 v[24:27], v34 offset:13056
	ds_read_b128 v[32:35], v34 offset:13072
	s_waitcnt lgkmcnt(1)
	v_cvt_pk_bf16_f32 v24, v24, v25
	v_cvt_pk_bf16_f32 v25, v26, v27
	s_waitcnt lgkmcnt(0)
	v_cvt_pk_bf16_f32 v26, v32, v33
	v_cvt_pk_bf16_f32 v27, v34, v35
	s_nop 1
	v_mfma_f32_16x16x32_bf16 v[32:35], v[24:27], v[42:45], 0
	v_mfma_f32_16x16x32_bf16 v[24:27], v[24:27], v[28:31], 0
	s_nop 6
	v_cvt_pk_bf16_f32 v32, v32, v33
	v_cvt_pk_bf16_f32 v33, v34, v35
	ds_write_b64 v46, v[32:33] offset:32
	v_cvt_pk_bf16_f32 v24, v24, v25
	v_cvt_pk_bf16_f32 v25, v26, v27
	ds_write_b64 v47, v[24:25] offset:32
	v_lshlrev_b32_e32 v24, 7, v185
	v_sub_u32_e32 v24, v38, v24
	v_add_u32_e32 v24, v24, v40
	s_waitcnt lgkmcnt(0)
	ds_read_b128 v[24:27], v24 offset:22080
	v_add_u32_e32 v38, s67, v40
	v_mad_u32_u24 v28, v185, s69, v38
	ds_read_b128 v[28:31], v28
	s_waitcnt lgkmcnt(0)
	v_mfma_f32_16x16x32_bf16 v[32:35], v[24:27], v[28:31], 0
	s_nop 7
	v_cvt_pk_bf16_f32 v32, -v32, s0
	ds_write_b16 v37, v32 offset:22016
	v_cvt_pk_bf16_f32 v32, -v33, s0
	ds_write_b16 v37, v32 offset:22160
	v_cvt_pk_bf16_f32 v32, -v34, s0
	ds_write_b16 v37, v32 offset:22304
	v_cvt_pk_bf16_f32 v32, -v35, s0
	ds_write_b16 v37, v32 offset:22448
	v_add_u32_e32 v32, v38, v39
	ds_read_b128 v[32:35], v32
	s_waitcnt lgkmcnt(0)
	v_mfma_f32_16x16x32_bf16 v[24:27], v[24:27], v[32:35], 0
	s_nop 7
	v_cvt_pk_bf16_f32 v24, -v24, s0
	ds_write_b16 v37, v24 offset:22048
	v_cvt_pk_bf16_f32 v24, -v25, s0
	ds_write_b16 v37, v24 offset:22192
	v_cvt_pk_bf16_f32 v24, -v26, s0
	ds_write_b16 v37, v24 offset:22336
	v_cvt_pk_bf16_f32 v24, -v27, s0
	ds_write_b16 v37, v24 offset:22480
	v_add3_u32 v24, 0, v36, v40
	ds_read_b128 v[24:27], v24 offset:17472
	s_waitcnt lgkmcnt(0)
	v_mfma_f32_16x16x32_bf16 v[28:31], v[24:27], v[28:31], 0
	s_nop 7
	v_cvt_pk_bf16_f32 v28, -v28, s0
	v_mfma_f32_16x16x32_bf16 v[24:27], v[24:27], v[32:35], 0
	v_cvt_pk_bf16_f32 v29, -v29, s0
	ds_write_b16 v37, v28 offset:24320
	ds_write_b16 v37, v29 offset:24464
	v_cvt_pk_bf16_f32 v28, -v30, s0
	ds_write_b16 v37, v28 offset:24608
	s_nop 2
	v_cvt_pk_bf16_f32 v24, -v24, s0
	ds_write_b16 v37, v24 offset:24352
	v_cvt_pk_bf16_f32 v24, -v25, s0
	ds_write_b16 v37, v24 offset:24496
	v_cvt_pk_bf16_f32 v24, -v26, s0
	v_cvt_pk_bf16_f32 v28, -v31, s0
	ds_write_b16 v37, v24 offset:24640
	v_cvt_pk_bf16_f32 v24, -v27, s0
	ds_write_b16 v37, v28 offset:24752
	ds_write_b16 v37, v24 offset:24784
	s_waitcnt lgkmcnt(0)
	s_setprio 0
	s_barrier
